# v38 + ssm_scan carry recurrence unrolled with E loads prefetched 12 chunks ahead (was 64 dependent round trips on 16 workgroups)
# speedup vs baseline: 1.0173x; 1.0030x over previous
; __device__ __forceinline__ unsigned f2bf(float f) { return pk2(f, 0.f) & 0xffffu; }
; __device__ __forceinline__ void ssm_scan(const Args& a, int id) {
;     ...
;     float hr = 0.f, hi = 0.f;
; #pragma unroll 8
;     for (int n = 0; n < 64; ++n) {
;         const size_t base = ((size_t)(b * 64 + n) * 32 + g) * 128;
;         HC[base + p] = (bf16_t)f2bf(hr); HC[base + 64 + p] = (bf16_t)f2bf(hi);
;         const float er = E[base + p], ei = E[base + 64 + p];
;         const float nr = lr * hr - li * hi + er, ni = lr * hi + li * hr + ei;
;         hr = nr; hi = ni;
;     }
.LBB0_328:
	s_mov_b32 s101, 0
	v_lshl_add_u64 v[24:25], s[82:83], 0, v[4:5]
	s_mov_b32 s100, 0x500000
	v_lshl_add_u64 v[24:25], v[24:25], 0, s[100:101]
	v_lshl_add_u64 v[26:27], s[82:83], 0, v[6:7]
	s_mov_b32 s100, 0x900000
	v_lshl_add_u64 v[26:27], v[26:27], 0, s[100:101]
	s_mov_b32 s100, 0x0
	v_lshl_add_u64 v[28:29], v[24:25], 0, s[100:101]
	global_load_dword v32, v[28:29], off
	global_load_dword v33, v[28:29], off offset:256
	s_mov_b32 s100, 0x4000
	v_lshl_add_u64 v[28:29], v[24:25], 0, s[100:101]
	global_load_dword v34, v[28:29], off
	global_load_dword v35, v[28:29], off offset:256
	s_mov_b32 s100, 0x8000
	v_lshl_add_u64 v[28:29], v[24:25], 0, s[100:101]
	global_load_dword v36, v[28:29], off
	global_load_dword v37, v[28:29], off offset:256
	s_mov_b32 s100, 0xc000
	v_lshl_add_u64 v[28:29], v[24:25], 0, s[100:101]
	global_load_dword v38, v[28:29], off
	global_load_dword v39, v[28:29], off offset:256
	s_mov_b32 s100, 0x10000
	v_lshl_add_u64 v[28:29], v[24:25], 0, s[100:101]
	global_load_dword v40, v[28:29], off
	global_load_dword v41, v[28:29], off offset:256
	s_mov_b32 s100, 0x14000
	v_lshl_add_u64 v[28:29], v[24:25], 0, s[100:101]
	global_load_dword v42, v[28:29], off
	global_load_dword v43, v[28:29], off offset:256
	s_mov_b32 s100, 0x18000
	v_lshl_add_u64 v[28:29], v[24:25], 0, s[100:101]
	global_load_dword v44, v[28:29], off
	global_load_dword v45, v[28:29], off offset:256
	s_mov_b32 s100, 0x1c000
	v_lshl_add_u64 v[28:29], v[24:25], 0, s[100:101]
	global_load_dword v46, v[28:29], off
	global_load_dword v47, v[28:29], off offset:256
	s_mov_b32 s100, 0x20000
	v_lshl_add_u64 v[28:29], v[24:25], 0, s[100:101]
	global_load_dword v48, v[28:29], off
	global_load_dword v49, v[28:29], off offset:256
	s_mov_b32 s100, 0x24000
	v_lshl_add_u64 v[28:29], v[24:25], 0, s[100:101]
	global_load_dword v50, v[28:29], off
	global_load_dword v51, v[28:29], off offset:256
	s_mov_b32 s100, 0x28000
	v_lshl_add_u64 v[28:29], v[24:25], 0, s[100:101]
	global_load_dword v52, v[28:29], off
	global_load_dword v53, v[28:29], off offset:256
	s_mov_b32 s100, 0x2c000
	v_lshl_add_u64 v[28:29], v[24:25], 0, s[100:101]
	global_load_dword v54, v[28:29], off
	global_load_dword v55, v[28:29], off offset:256
	s_mov_b32 s100, 0x0
	v_lshl_add_u64 v[30:31], v[26:27], 0, s[100:101]
	v_cvt_pk_bf16_f32 v14, v8, s0
	v_cvt_pk_bf16_f32 v15, v9, s0
	global_store_short v[30:31], v14, off
	global_store_short v[30:31], v15, off offset:128
	v_pk_mul_f32 v[16:17], v[2:3], v[8:9] op_sel:[0,1]
	s_nop 0
	v_pk_fma_f32 v[18:19], v[0:1], v[8:9], v[16:17] neg_lo:[0,0,1] neg_hi:[0,0,1]
	v_pk_fma_f32 v[8:9], v[0:1], v[8:9], v[16:17] op_sel_hi:[1,0,1]
	v_mov_b32_e32 v19, v9
	s_waitcnt vmcnt(24)
	v_pk_add_f32 v[8:9], v[18:19], v[32:33]
	s_mov_b32 s100, 0x30000
	v_lshl_add_u64 v[28:29], v[24:25], 0, s[100:101]
	global_load_dword v32, v[28:29], off
	global_load_dword v33, v[28:29], off offset:256
	s_mov_b32 s100, 0x2000
	v_lshl_add_u64 v[30:31], v[26:27], 0, s[100:101]
	v_cvt_pk_bf16_f32 v14, v8, s0
	v_cvt_pk_bf16_f32 v15, v9, s0
	global_store_short v[30:31], v14, off
	global_store_short v[30:31], v15, off offset:128
	v_pk_mul_f32 v[16:17], v[2:3], v[8:9] op_sel:[0,1]
	s_nop 0
	v_pk_fma_f32 v[18:19], v[0:1], v[8:9], v[16:17] neg_lo:[0,0,1] neg_hi:[0,0,1]
	v_pk_fma_f32 v[8:9], v[0:1], v[8:9], v[16:17] op_sel_hi:[1,0,1]
	v_mov_b32_e32 v19, v9
	s_waitcnt vmcnt(26)
	v_pk_add_f32 v[8:9], v[18:19], v[34:35]
	s_mov_b32 s100, 0x34000
	v_lshl_add_u64 v[28:29], v[24:25], 0, s[100:101]
	global_load_dword v34, v[28:29], off
	global_load_dword v35, v[28:29], off offset:256
	s_mov_b32 s100, 0x4000
	v_lshl_add_u64 v[30:31], v[26:27], 0, s[100:101]
	v_cvt_pk_bf16_f32 v14, v8, s0
	v_cvt_pk_bf16_f32 v15, v9, s0
	global_store_short v[30:31], v14, off
	global_store_short v[30:31], v15, off offset:128
	v_pk_mul_f32 v[16:17], v[2:3], v[8:9] op_sel:[0,1]
	s_nop 0
	v_pk_fma_f32 v[18:19], v[0:1], v[8:9], v[16:17] neg_lo:[0,0,1] neg_hi:[0,0,1]
	v_pk_fma_f32 v[8:9], v[0:1], v[8:9], v[16:17] op_sel_hi:[1,0,1]
	v_mov_b32_e32 v19, v9
	s_waitcnt vmcnt(28)
	v_pk_add_f32 v[8:9], v[18:19], v[36:37]
	s_mov_b32 s100, 0x38000
	v_lshl_add_u64 v[28:29], v[24:25], 0, s[100:101]
	global_load_dword v36, v[28:29], off
	global_load_dword v37, v[28:29], off offset:256
	s_mov_b32 s100, 0x6000
	v_lshl_add_u64 v[30:31], v[26:27], 0, s[100:101]
	v_cvt_pk_bf16_f32 v14, v8, s0
	v_cvt_pk_bf16_f32 v15, v9, s0
	global_store_short v[30:31], v14, off
	global_store_short v[30:31], v15, off offset:128
	v_pk_mul_f32 v[16:17], v[2:3], v[8:9] op_sel:[0,1]
	s_nop 0
	v_pk_fma_f32 v[18:19], v[0:1], v[8:9], v[16:17] neg_lo:[0,0,1] neg_hi:[0,0,1]
	v_pk_fma_f32 v[8:9], v[0:1], v[8:9], v[16:17] op_sel_hi:[1,0,1]
	v_mov_b32_e32 v19, v9
	s_waitcnt vmcnt(30)
	v_pk_add_f32 v[8:9], v[18:19], v[38:39]
	s_mov_b32 s100, 0x3c000
	v_lshl_add_u64 v[28:29], v[24:25], 0, s[100:101]
	global_load_dword v38, v[28:29], off
	global_load_dword v39, v[28:29], off offset:256
	s_mov_b32 s100, 0x8000
	v_lshl_add_u64 v[30:31], v[26:27], 0, s[100:101]
	v_cvt_pk_bf16_f32 v14, v8, s0
	v_cvt_pk_bf16_f32 v15, v9, s0
	global_store_short v[30:31], v14, off
	global_store_short v[30:31], v15, off offset:128
	v_pk_mul_f32 v[16:17], v[2:3], v[8:9] op_sel:[0,1]
	s_nop 0
	v_pk_fma_f32 v[18:19], v[0:1], v[8:9], v[16:17] neg_lo:[0,0,1] neg_hi:[0,0,1]
	v_pk_fma_f32 v[8:9], v[0:1], v[8:9], v[16:17] op_sel_hi:[1,0,1]
	v_mov_b32_e32 v19, v9
	s_waitcnt vmcnt(32)
; __device__ __forceinline__ unsigned f2bf(float f) { return pk2(f, 0.f) & 0xffffu; }
; __device__ __forceinline__ void ssm_scan(const Args& a, int id) {
;     ...
;     float hr = 0.f, hi = 0.f;
; #pragma unroll 8
;     for (int n = 0; n < 64; ++n) {
;         const size_t base = ((size_t)(b * 64 + n) * 32 + g) * 128;
;         HC[base + p] = (bf16_t)f2bf(hr); HC[base + 64 + p] = (bf16_t)f2bf(hi);
;         const float er = E[base + p], ei = E[base + 64 + p];
;         const float nr = lr * hr - li * hi + er, ni = lr * hi + li * hr + ei;
;         hr = nr; hi = ni;
;     }
	v_pk_add_f32 v[8:9], v[18:19], v[40:41]
	s_mov_b32 s100, 0x40000
	v_lshl_add_u64 v[28:29], v[24:25], 0, s[100:101]
	global_load_dword v40, v[28:29], off
	global_load_dword v41, v[28:29], off offset:256
	s_mov_b32 s100, 0xa000
	v_lshl_add_u64 v[30:31], v[26:27], 0, s[100:101]
	v_cvt_pk_bf16_f32 v14, v8, s0
	v_cvt_pk_bf16_f32 v15, v9, s0
	global_store_short v[30:31], v14, off
	global_store_short v[30:31], v15, off offset:128
	v_pk_mul_f32 v[16:17], v[2:3], v[8:9] op_sel:[0,1]
	s_nop 0
	v_pk_fma_f32 v[18:19], v[0:1], v[8:9], v[16:17] neg_lo:[0,0,1] neg_hi:[0,0,1]
	v_pk_fma_f32 v[8:9], v[0:1], v[8:9], v[16:17] op_sel_hi:[1,0,1]
	v_mov_b32_e32 v19, v9
	s_waitcnt vmcnt(34)
	v_pk_add_f32 v[8:9], v[18:19], v[42:43]
	s_mov_b32 s100, 0x44000
	v_lshl_add_u64 v[28:29], v[24:25], 0, s[100:101]
	global_load_dword v42, v[28:29], off
	global_load_dword v43, v[28:29], off offset:256
	s_mov_b32 s100, 0xc000
	v_lshl_add_u64 v[30:31], v[26:27], 0, s[100:101]
	v_cvt_pk_bf16_f32 v14, v8, s0
	v_cvt_pk_bf16_f32 v15, v9, s0
	global_store_short v[30:31], v14, off
	global_store_short v[30:31], v15, off offset:128
	v_pk_mul_f32 v[16:17], v[2:3], v[8:9] op_sel:[0,1]
	s_nop 0
	v_pk_fma_f32 v[18:19], v[0:1], v[8:9], v[16:17] neg_lo:[0,0,1] neg_hi:[0,0,1]
	v_pk_fma_f32 v[8:9], v[0:1], v[8:9], v[16:17] op_sel_hi:[1,0,1]
	v_mov_b32_e32 v19, v9
	s_waitcnt vmcnt(36)
	v_pk_add_f32 v[8:9], v[18:19], v[44:45]
	s_mov_b32 s100, 0x48000
	v_lshl_add_u64 v[28:29], v[24:25], 0, s[100:101]
	global_load_dword v44, v[28:29], off
	global_load_dword v45, v[28:29], off offset:256
	s_mov_b32 s100, 0xe000
	v_lshl_add_u64 v[30:31], v[26:27], 0, s[100:101]
	v_cvt_pk_bf16_f32 v14, v8, s0
	v_cvt_pk_bf16_f32 v15, v9, s0
	global_store_short v[30:31], v14, off
	global_store_short v[30:31], v15, off offset:128
	v_pk_mul_f32 v[16:17], v[2:3], v[8:9] op_sel:[0,1]
	s_nop 0
	v_pk_fma_f32 v[18:19], v[0:1], v[8:9], v[16:17] neg_lo:[0,0,1] neg_hi:[0,0,1]
	v_pk_fma_f32 v[8:9], v[0:1], v[8:9], v[16:17] op_sel_hi:[1,0,1]
	v_mov_b32_e32 v19, v9
	s_waitcnt vmcnt(38)
	v_pk_add_f32 v[8:9], v[18:19], v[46:47]
	s_mov_b32 s100, 0x4c000
	v_lshl_add_u64 v[28:29], v[24:25], 0, s[100:101]
	global_load_dword v46, v[28:29], off
	global_load_dword v47, v[28:29], off offset:256
	s_mov_b32 s100, 0x10000
	v_lshl_add_u64 v[30:31], v[26:27], 0, s[100:101]
	v_cvt_pk_bf16_f32 v14, v8, s0
	v_cvt_pk_bf16_f32 v15, v9, s0
	global_store_short v[30:31], v14, off
	global_store_short v[30:31], v15, off offset:128
	v_pk_mul_f32 v[16:17], v[2:3], v[8:9] op_sel:[0,1]
	s_nop 0
	v_pk_fma_f32 v[18:19], v[0:1], v[8:9], v[16:17] neg_lo:[0,0,1] neg_hi:[0,0,1]
	v_pk_fma_f32 v[8:9], v[0:1], v[8:9], v[16:17] op_sel_hi:[1,0,1]
	v_mov_b32_e32 v19, v9
	s_waitcnt vmcnt(40)
	v_pk_add_f32 v[8:9], v[18:19], v[48:49]
	s_mov_b32 s100, 0x50000
	v_lshl_add_u64 v[28:29], v[24:25], 0, s[100:101]
	global_load_dword v48, v[28:29], off
	global_load_dword v49, v[28:29], off offset:256
	s_mov_b32 s100, 0x12000
	v_lshl_add_u64 v[30:31], v[26:27], 0, s[100:101]
	v_cvt_pk_bf16_f32 v14, v8, s0
	v_cvt_pk_bf16_f32 v15, v9, s0
	global_store_short v[30:31], v14, off
	global_store_short v[30:31], v15, off offset:128
	v_pk_mul_f32 v[16:17], v[2:3], v[8:9] op_sel:[0,1]
	s_nop 0
	v_pk_fma_f32 v[18:19], v[0:1], v[8:9], v[16:17] neg_lo:[0,0,1] neg_hi:[0,0,1]
	v_pk_fma_f32 v[8:9], v[0:1], v[8:9], v[16:17] op_sel_hi:[1,0,1]
	v_mov_b32_e32 v19, v9
	s_waitcnt vmcnt(42)
	v_pk_add_f32 v[8:9], v[18:19], v[50:51]
	s_mov_b32 s100, 0x54000
	v_lshl_add_u64 v[28:29], v[24:25], 0, s[100:101]
	global_load_dword v50, v[28:29], off
	global_load_dword v51, v[28:29], off offset:256
	s_mov_b32 s100, 0x14000
	v_lshl_add_u64 v[30:31], v[26:27], 0, s[100:101]
	v_cvt_pk_bf16_f32 v14, v8, s0
	v_cvt_pk_bf16_f32 v15, v9, s0
	global_store_short v[30:31], v14, off
	global_store_short v[30:31], v15, off offset:128
	v_pk_mul_f32 v[16:17], v[2:3], v[8:9] op_sel:[0,1]
	s_nop 0
	v_pk_fma_f32 v[18:19], v[0:1], v[8:9], v[16:17] neg_lo:[0,0,1] neg_hi:[0,0,1]
	v_pk_fma_f32 v[8:9], v[0:1], v[8:9], v[16:17] op_sel_hi:[1,0,1]
	v_mov_b32_e32 v19, v9
	s_waitcnt vmcnt(44)
	v_pk_add_f32 v[8:9], v[18:19], v[52:53]
	s_mov_b32 s100, 0x58000
	v_lshl_add_u64 v[28:29], v[24:25], 0, s[100:101]
	global_load_dword v52, v[28:29], off
	global_load_dword v53, v[28:29], off offset:256
	s_mov_b32 s100, 0x16000
	v_lshl_add_u64 v[30:31], v[26:27], 0, s[100:101]
	v_cvt_pk_bf16_f32 v14, v8, s0
	v_cvt_pk_bf16_f32 v15, v9, s0
	global_store_short v[30:31], v14, off
	global_store_short v[30:31], v15, off offset:128
	v_pk_mul_f32 v[16:17], v[2:3], v[8:9] op_sel:[0,1]
	s_nop 0
	v_pk_fma_f32 v[18:19], v[0:1], v[8:9], v[16:17] neg_lo:[0,0,1] neg_hi:[0,0,1]
	v_pk_fma_f32 v[8:9], v[0:1], v[8:9], v[16:17] op_sel_hi:[1,0,1]
	v_mov_b32_e32 v19, v9
	s_waitcnt vmcnt(46)
	v_pk_add_f32 v[8:9], v[18:19], v[54:55]
	s_mov_b32 s100, 0x5c000
	v_lshl_add_u64 v[28:29], v[24:25], 0, s[100:101]
	global_load_dword v54, v[28:29], off
	global_load_dword v55, v[28:29], off offset:256
	s_mov_b32 s100, 0x18000
	v_lshl_add_u64 v[30:31], v[26:27], 0, s[100:101]
	v_cvt_pk_bf16_f32 v14, v8, s0
	v_cvt_pk_bf16_f32 v15, v9, s0
	global_store_short v[30:31], v14, off
	global_store_short v[30:31], v15, off offset:128
	v_pk_mul_f32 v[16:17], v[2:3], v[8:9] op_sel:[0,1]
	s_nop 0
	v_pk_fma_f32 v[18:19], v[0:1], v[8:9], v[16:17] neg_lo:[0,0,1] neg_hi:[0,0,1]
	v_pk_fma_f32 v[8:9], v[0:1], v[8:9], v[16:17] op_sel_hi:[1,0,1]
	v_mov_b32_e32 v19, v9
	s_waitcnt vmcnt(46)
; __device__ __forceinline__ unsigned f2bf(float f) { return pk2(f, 0.f) & 0xffffu; }
; __device__ __forceinline__ void ssm_scan(const Args& a, int id) {
;     ...
;     float hr = 0.f, hi = 0.f;
; #pragma unroll 8
;     for (int n = 0; n < 64; ++n) {
;         const size_t base = ((size_t)(b * 64 + n) * 32 + g) * 128;
;         HC[base + p] = (bf16_t)f2bf(hr); HC[base + 64 + p] = (bf16_t)f2bf(hi);
;         const float er = E[base + p], ei = E[base + 64 + p];
;         const float nr = lr * hr - li * hi + er, ni = lr * hi + li * hr + ei;
;         hr = nr; hi = ni;
;     }
	v_pk_add_f32 v[8:9], v[18:19], v[32:33]
	s_mov_b32 s100, 0x60000
	v_lshl_add_u64 v[28:29], v[24:25], 0, s[100:101]
	global_load_dword v32, v[28:29], off
	global_load_dword v33, v[28:29], off offset:256
	s_mov_b32 s100, 0x1a000
	v_lshl_add_u64 v[30:31], v[26:27], 0, s[100:101]
	v_cvt_pk_bf16_f32 v14, v8, s0
	v_cvt_pk_bf16_f32 v15, v9, s0
	global_store_short v[30:31], v14, off
	global_store_short v[30:31], v15, off offset:128
	v_pk_mul_f32 v[16:17], v[2:3], v[8:9] op_sel:[0,1]
	s_nop 0
	v_pk_fma_f32 v[18:19], v[0:1], v[8:9], v[16:17] neg_lo:[0,0,1] neg_hi:[0,0,1]
	v_pk_fma_f32 v[8:9], v[0:1], v[8:9], v[16:17] op_sel_hi:[1,0,1]
	v_mov_b32_e32 v19, v9
	s_waitcnt vmcnt(46)
	v_pk_add_f32 v[8:9], v[18:19], v[34:35]
	s_mov_b32 s100, 0x64000
	v_lshl_add_u64 v[28:29], v[24:25], 0, s[100:101]
	global_load_dword v34, v[28:29], off
	global_load_dword v35, v[28:29], off offset:256
	s_mov_b32 s100, 0x1c000
	v_lshl_add_u64 v[30:31], v[26:27], 0, s[100:101]
	v_cvt_pk_bf16_f32 v14, v8, s0
	v_cvt_pk_bf16_f32 v15, v9, s0
	global_store_short v[30:31], v14, off
	global_store_short v[30:31], v15, off offset:128
	v_pk_mul_f32 v[16:17], v[2:3], v[8:9] op_sel:[0,1]
	s_nop 0
	v_pk_fma_f32 v[18:19], v[0:1], v[8:9], v[16:17] neg_lo:[0,0,1] neg_hi:[0,0,1]
	v_pk_fma_f32 v[8:9], v[0:1], v[8:9], v[16:17] op_sel_hi:[1,0,1]
	v_mov_b32_e32 v19, v9
	s_waitcnt vmcnt(46)
	v_pk_add_f32 v[8:9], v[18:19], v[36:37]
	s_mov_b32 s100, 0x68000
	v_lshl_add_u64 v[28:29], v[24:25], 0, s[100:101]
	global_load_dword v36, v[28:29], off
	global_load_dword v37, v[28:29], off offset:256
	s_mov_b32 s100, 0x1e000
	v_lshl_add_u64 v[30:31], v[26:27], 0, s[100:101]
	v_cvt_pk_bf16_f32 v14, v8, s0
	v_cvt_pk_bf16_f32 v15, v9, s0
	global_store_short v[30:31], v14, off
	global_store_short v[30:31], v15, off offset:128
	v_pk_mul_f32 v[16:17], v[2:3], v[8:9] op_sel:[0,1]
	s_nop 0
	v_pk_fma_f32 v[18:19], v[0:1], v[8:9], v[16:17] neg_lo:[0,0,1] neg_hi:[0,0,1]
	v_pk_fma_f32 v[8:9], v[0:1], v[8:9], v[16:17] op_sel_hi:[1,0,1]
	v_mov_b32_e32 v19, v9
	s_waitcnt vmcnt(46)
	v_pk_add_f32 v[8:9], v[18:19], v[38:39]
	s_mov_b32 s100, 0x6c000
	v_lshl_add_u64 v[28:29], v[24:25], 0, s[100:101]
	global_load_dword v38, v[28:29], off
	global_load_dword v39, v[28:29], off offset:256
	s_mov_b32 s100, 0x20000
	v_lshl_add_u64 v[30:31], v[26:27], 0, s[100:101]
	v_cvt_pk_bf16_f32 v14, v8, s0
	v_cvt_pk_bf16_f32 v15, v9, s0
	global_store_short v[30:31], v14, off
	global_store_short v[30:31], v15, off offset:128
	v_pk_mul_f32 v[16:17], v[2:3], v[8:9] op_sel:[0,1]
	s_nop 0
	v_pk_fma_f32 v[18:19], v[0:1], v[8:9], v[16:17] neg_lo:[0,0,1] neg_hi:[0,0,1]
	v_pk_fma_f32 v[8:9], v[0:1], v[8:9], v[16:17] op_sel_hi:[1,0,1]
	v_mov_b32_e32 v19, v9
	s_waitcnt vmcnt(46)
	v_pk_add_f32 v[8:9], v[18:19], v[40:41]
	s_mov_b32 s100, 0x70000
	v_lshl_add_u64 v[28:29], v[24:25], 0, s[100:101]
	global_load_dword v40, v[28:29], off
	global_load_dword v41, v[28:29], off offset:256
	s_mov_b32 s100, 0x22000
	v_lshl_add_u64 v[30:31], v[26:27], 0, s[100:101]
	v_cvt_pk_bf16_f32 v14, v8, s0
	v_cvt_pk_bf16_f32 v15, v9, s0
	global_store_short v[30:31], v14, off
	global_store_short v[30:31], v15, off offset:128
	v_pk_mul_f32 v[16:17], v[2:3], v[8:9] op_sel:[0,1]
	s_nop 0
	v_pk_fma_f32 v[18:19], v[0:1], v[8:9], v[16:17] neg_lo:[0,0,1] neg_hi:[0,0,1]
	v_pk_fma_f32 v[8:9], v[0:1], v[8:9], v[16:17] op_sel_hi:[1,0,1]
	v_mov_b32_e32 v19, v9
	s_waitcnt vmcnt(46)
	v_pk_add_f32 v[8:9], v[18:19], v[42:43]
	s_mov_b32 s100, 0x74000
	v_lshl_add_u64 v[28:29], v[24:25], 0, s[100:101]
	global_load_dword v42, v[28:29], off
	global_load_dword v43, v[28:29], off offset:256
	s_mov_b32 s100, 0x24000
	v_lshl_add_u64 v[30:31], v[26:27], 0, s[100:101]
	v_cvt_pk_bf16_f32 v14, v8, s0
	v_cvt_pk_bf16_f32 v15, v9, s0
	global_store_short v[30:31], v14, off
	global_store_short v[30:31], v15, off offset:128
	v_pk_mul_f32 v[16:17], v[2:3], v[8:9] op_sel:[0,1]
	s_nop 0
	v_pk_fma_f32 v[18:19], v[0:1], v[8:9], v[16:17] neg_lo:[0,0,1] neg_hi:[0,0,1]
	v_pk_fma_f32 v[8:9], v[0:1], v[8:9], v[16:17] op_sel_hi:[1,0,1]
	v_mov_b32_e32 v19, v9
	s_waitcnt vmcnt(46)
	v_pk_add_f32 v[8:9], v[18:19], v[44:45]
	s_mov_b32 s100, 0x78000
	v_lshl_add_u64 v[28:29], v[24:25], 0, s[100:101]
	global_load_dword v44, v[28:29], off
	global_load_dword v45, v[28:29], off offset:256
	s_mov_b32 s100, 0x26000
	v_lshl_add_u64 v[30:31], v[26:27], 0, s[100:101]
	v_cvt_pk_bf16_f32 v14, v8, s0
	v_cvt_pk_bf16_f32 v15, v9, s0
	global_store_short v[30:31], v14, off
	global_store_short v[30:31], v15, off offset:128
	v_pk_mul_f32 v[16:17], v[2:3], v[8:9] op_sel:[0,1]
	s_nop 0
	v_pk_fma_f32 v[18:19], v[0:1], v[8:9], v[16:17] neg_lo:[0,0,1] neg_hi:[0,0,1]
	v_pk_fma_f32 v[8:9], v[0:1], v[8:9], v[16:17] op_sel_hi:[1,0,1]
	v_mov_b32_e32 v19, v9
	s_waitcnt vmcnt(46)
	v_pk_add_f32 v[8:9], v[18:19], v[46:47]
	s_mov_b32 s100, 0x7c000
	v_lshl_add_u64 v[28:29], v[24:25], 0, s[100:101]
	global_load_dword v46, v[28:29], off
	global_load_dword v47, v[28:29], off offset:256
	s_mov_b32 s100, 0x28000
	v_lshl_add_u64 v[30:31], v[26:27], 0, s[100:101]
	v_cvt_pk_bf16_f32 v14, v8, s0
	v_cvt_pk_bf16_f32 v15, v9, s0
	global_store_short v[30:31], v14, off
	global_store_short v[30:31], v15, off offset:128
	v_pk_mul_f32 v[16:17], v[2:3], v[8:9] op_sel:[0,1]
	s_nop 0
	v_pk_fma_f32 v[18:19], v[0:1], v[8:9], v[16:17] neg_lo:[0,0,1] neg_hi:[0,0,1]
	v_pk_fma_f32 v[8:9], v[0:1], v[8:9], v[16:17] op_sel_hi:[1,0,1]
	v_mov_b32_e32 v19, v9
	s_waitcnt vmcnt(46)
; __device__ __forceinline__ unsigned f2bf(float f) { return pk2(f, 0.f) & 0xffffu; }
; __device__ __forceinline__ void ssm_scan(const Args& a, int id) {
;     ...
;     float hr = 0.f, hi = 0.f;
; #pragma unroll 8
;     for (int n = 0; n < 64; ++n) {
;         const size_t base = ((size_t)(b * 64 + n) * 32 + g) * 128;
;         HC[base + p] = (bf16_t)f2bf(hr); HC[base + 64 + p] = (bf16_t)f2bf(hi);
;         const float er = E[base + p], ei = E[base + 64 + p];
;         const float nr = lr * hr - li * hi + er, ni = lr * hi + li * hr + ei;
;         hr = nr; hi = ni;
;     }
	v_pk_add_f32 v[8:9], v[18:19], v[48:49]
	s_mov_b32 s100, 0x80000
	v_lshl_add_u64 v[28:29], v[24:25], 0, s[100:101]
	global_load_dword v48, v[28:29], off
	global_load_dword v49, v[28:29], off offset:256
	s_mov_b32 s100, 0x2a000
	v_lshl_add_u64 v[30:31], v[26:27], 0, s[100:101]
	v_cvt_pk_bf16_f32 v14, v8, s0
	v_cvt_pk_bf16_f32 v15, v9, s0
	global_store_short v[30:31], v14, off
	global_store_short v[30:31], v15, off offset:128
	v_pk_mul_f32 v[16:17], v[2:3], v[8:9] op_sel:[0,1]
	s_nop 0
	v_pk_fma_f32 v[18:19], v[0:1], v[8:9], v[16:17] neg_lo:[0,0,1] neg_hi:[0,0,1]
	v_pk_fma_f32 v[8:9], v[0:1], v[8:9], v[16:17] op_sel_hi:[1,0,1]
	v_mov_b32_e32 v19, v9
	s_waitcnt vmcnt(46)
	v_pk_add_f32 v[8:9], v[18:19], v[50:51]
	s_mov_b32 s100, 0x84000
	v_lshl_add_u64 v[28:29], v[24:25], 0, s[100:101]
	global_load_dword v50, v[28:29], off
	global_load_dword v51, v[28:29], off offset:256
	s_mov_b32 s100, 0x2c000
	v_lshl_add_u64 v[30:31], v[26:27], 0, s[100:101]
	v_cvt_pk_bf16_f32 v14, v8, s0
	v_cvt_pk_bf16_f32 v15, v9, s0
	global_store_short v[30:31], v14, off
	global_store_short v[30:31], v15, off offset:128
	v_pk_mul_f32 v[16:17], v[2:3], v[8:9] op_sel:[0,1]
	s_nop 0
	v_pk_fma_f32 v[18:19], v[0:1], v[8:9], v[16:17] neg_lo:[0,0,1] neg_hi:[0,0,1]
	v_pk_fma_f32 v[8:9], v[0:1], v[8:9], v[16:17] op_sel_hi:[1,0,1]
	v_mov_b32_e32 v19, v9
	s_waitcnt vmcnt(46)
	v_pk_add_f32 v[8:9], v[18:19], v[52:53]
	s_mov_b32 s100, 0x88000
	v_lshl_add_u64 v[28:29], v[24:25], 0, s[100:101]
	global_load_dword v52, v[28:29], off
	global_load_dword v53, v[28:29], off offset:256
	s_mov_b32 s100, 0x2e000
	v_lshl_add_u64 v[30:31], v[26:27], 0, s[100:101]
	v_cvt_pk_bf16_f32 v14, v8, s0
	v_cvt_pk_bf16_f32 v15, v9, s0
	global_store_short v[30:31], v14, off
	global_store_short v[30:31], v15, off offset:128
	v_pk_mul_f32 v[16:17], v[2:3], v[8:9] op_sel:[0,1]
	s_nop 0
	v_pk_fma_f32 v[18:19], v[0:1], v[8:9], v[16:17] neg_lo:[0,0,1] neg_hi:[0,0,1]
	v_pk_fma_f32 v[8:9], v[0:1], v[8:9], v[16:17] op_sel_hi:[1,0,1]
	v_mov_b32_e32 v19, v9
	s_waitcnt vmcnt(46)
	v_pk_add_f32 v[8:9], v[18:19], v[54:55]
	s_mov_b32 s100, 0x8c000
	v_lshl_add_u64 v[28:29], v[24:25], 0, s[100:101]
	global_load_dword v54, v[28:29], off
	global_load_dword v55, v[28:29], off offset:256
	s_mov_b32 s100, 0x30000
	v_lshl_add_u64 v[30:31], v[26:27], 0, s[100:101]
	v_cvt_pk_bf16_f32 v14, v8, s0
	v_cvt_pk_bf16_f32 v15, v9, s0
	global_store_short v[30:31], v14, off
	global_store_short v[30:31], v15, off offset:128
	v_pk_mul_f32 v[16:17], v[2:3], v[8:9] op_sel:[0,1]
	s_nop 0
	v_pk_fma_f32 v[18:19], v[0:1], v[8:9], v[16:17] neg_lo:[0,0,1] neg_hi:[0,0,1]
	v_pk_fma_f32 v[8:9], v[0:1], v[8:9], v[16:17] op_sel_hi:[1,0,1]
	v_mov_b32_e32 v19, v9
	s_waitcnt vmcnt(46)
	v_pk_add_f32 v[8:9], v[18:19], v[32:33]
	s_mov_b32 s100, 0x90000
	v_lshl_add_u64 v[28:29], v[24:25], 0, s[100:101]
	global_load_dword v32, v[28:29], off
	global_load_dword v33, v[28:29], off offset:256
	s_mov_b32 s100, 0x32000
	v_lshl_add_u64 v[30:31], v[26:27], 0, s[100:101]
	v_cvt_pk_bf16_f32 v14, v8, s0
	v_cvt_pk_bf16_f32 v15, v9, s0
	global_store_short v[30:31], v14, off
	global_store_short v[30:31], v15, off offset:128
	v_pk_mul_f32 v[16:17], v[2:3], v[8:9] op_sel:[0,1]
	s_nop 0
	v_pk_fma_f32 v[18:19], v[0:1], v[8:9], v[16:17] neg_lo:[0,0,1] neg_hi:[0,0,1]
	v_pk_fma_f32 v[8:9], v[0:1], v[8:9], v[16:17] op_sel_hi:[1,0,1]
	v_mov_b32_e32 v19, v9
	s_waitcnt vmcnt(46)
	v_pk_add_f32 v[8:9], v[18:19], v[34:35]
	s_mov_b32 s100, 0x94000
	v_lshl_add_u64 v[28:29], v[24:25], 0, s[100:101]
	global_load_dword v34, v[28:29], off
	global_load_dword v35, v[28:29], off offset:256
	s_mov_b32 s100, 0x34000
	v_lshl_add_u64 v[30:31], v[26:27], 0, s[100:101]
	v_cvt_pk_bf16_f32 v14, v8, s0
	v_cvt_pk_bf16_f32 v15, v9, s0
	global_store_short v[30:31], v14, off
	global_store_short v[30:31], v15, off offset:128
	v_pk_mul_f32 v[16:17], v[2:3], v[8:9] op_sel:[0,1]
	s_nop 0
	v_pk_fma_f32 v[18:19], v[0:1], v[8:9], v[16:17] neg_lo:[0,0,1] neg_hi:[0,0,1]
	v_pk_fma_f32 v[8:9], v[0:1], v[8:9], v[16:17] op_sel_hi:[1,0,1]
	v_mov_b32_e32 v19, v9
	s_waitcnt vmcnt(46)
	v_pk_add_f32 v[8:9], v[18:19], v[36:37]
	s_mov_b32 s100, 0x98000
	v_lshl_add_u64 v[28:29], v[24:25], 0, s[100:101]
	global_load_dword v36, v[28:29], off
	global_load_dword v37, v[28:29], off offset:256
	s_mov_b32 s100, 0x36000
	v_lshl_add_u64 v[30:31], v[26:27], 0, s[100:101]
	v_cvt_pk_bf16_f32 v14, v8, s0
	v_cvt_pk_bf16_f32 v15, v9, s0
	global_store_short v[30:31], v14, off
	global_store_short v[30:31], v15, off offset:128
	v_pk_mul_f32 v[16:17], v[2:3], v[8:9] op_sel:[0,1]
	s_nop 0
	v_pk_fma_f32 v[18:19], v[0:1], v[8:9], v[16:17] neg_lo:[0,0,1] neg_hi:[0,0,1]
	v_pk_fma_f32 v[8:9], v[0:1], v[8:9], v[16:17] op_sel_hi:[1,0,1]
	v_mov_b32_e32 v19, v9
	s_waitcnt vmcnt(46)
	v_pk_add_f32 v[8:9], v[18:19], v[38:39]
	s_mov_b32 s100, 0x9c000
	v_lshl_add_u64 v[28:29], v[24:25], 0, s[100:101]
	global_load_dword v38, v[28:29], off
	global_load_dword v39, v[28:29], off offset:256
	s_mov_b32 s100, 0x38000
	v_lshl_add_u64 v[30:31], v[26:27], 0, s[100:101]
	v_cvt_pk_bf16_f32 v14, v8, s0
	v_cvt_pk_bf16_f32 v15, v9, s0
	global_store_short v[30:31], v14, off
	global_store_short v[30:31], v15, off offset:128
	v_pk_mul_f32 v[16:17], v[2:3], v[8:9] op_sel:[0,1]
	s_nop 0
	v_pk_fma_f32 v[18:19], v[0:1], v[8:9], v[16:17] neg_lo:[0,0,1] neg_hi:[0,0,1]
	v_pk_fma_f32 v[8:9], v[0:1], v[8:9], v[16:17] op_sel_hi:[1,0,1]
	v_mov_b32_e32 v19, v9
	s_waitcnt vmcnt(46)
; __device__ __forceinline__ unsigned f2bf(float f) { return pk2(f, 0.f) & 0xffffu; }
; __device__ __forceinline__ void ssm_scan(const Args& a, int id) {
;     ...
;     float hr = 0.f, hi = 0.f;
; #pragma unroll 8
;     for (int n = 0; n < 64; ++n) {
;         const size_t base = ((size_t)(b * 64 + n) * 32 + g) * 128;
;         HC[base + p] = (bf16_t)f2bf(hr); HC[base + 64 + p] = (bf16_t)f2bf(hi);
;         const float er = E[base + p], ei = E[base + 64 + p];
;         const float nr = lr * hr - li * hi + er, ni = lr * hi + li * hr + ei;
;         hr = nr; hi = ni;
;     }
	v_pk_add_f32 v[8:9], v[18:19], v[40:41]
	s_mov_b32 s100, 0xa0000
	v_lshl_add_u64 v[28:29], v[24:25], 0, s[100:101]
	global_load_dword v40, v[28:29], off
	global_load_dword v41, v[28:29], off offset:256
	s_mov_b32 s100, 0x3a000
	v_lshl_add_u64 v[30:31], v[26:27], 0, s[100:101]
	v_cvt_pk_bf16_f32 v14, v8, s0
	v_cvt_pk_bf16_f32 v15, v9, s0
	global_store_short v[30:31], v14, off
	global_store_short v[30:31], v15, off offset:128
	v_pk_mul_f32 v[16:17], v[2:3], v[8:9] op_sel:[0,1]
	s_nop 0
	v_pk_fma_f32 v[18:19], v[0:1], v[8:9], v[16:17] neg_lo:[0,0,1] neg_hi:[0,0,1]
	v_pk_fma_f32 v[8:9], v[0:1], v[8:9], v[16:17] op_sel_hi:[1,0,1]
	v_mov_b32_e32 v19, v9
	s_waitcnt vmcnt(46)
	v_pk_add_f32 v[8:9], v[18:19], v[42:43]
	s_mov_b32 s100, 0xa4000
	v_lshl_add_u64 v[28:29], v[24:25], 0, s[100:101]
	global_load_dword v42, v[28:29], off
	global_load_dword v43, v[28:29], off offset:256
	s_mov_b32 s100, 0x3c000
	v_lshl_add_u64 v[30:31], v[26:27], 0, s[100:101]
	v_cvt_pk_bf16_f32 v14, v8, s0
	v_cvt_pk_bf16_f32 v15, v9, s0
	global_store_short v[30:31], v14, off
	global_store_short v[30:31], v15, off offset:128
	v_pk_mul_f32 v[16:17], v[2:3], v[8:9] op_sel:[0,1]
	s_nop 0
	v_pk_fma_f32 v[18:19], v[0:1], v[8:9], v[16:17] neg_lo:[0,0,1] neg_hi:[0,0,1]
	v_pk_fma_f32 v[8:9], v[0:1], v[8:9], v[16:17] op_sel_hi:[1,0,1]
	v_mov_b32_e32 v19, v9
	s_waitcnt vmcnt(46)
	v_pk_add_f32 v[8:9], v[18:19], v[44:45]
	s_mov_b32 s100, 0xa8000
	v_lshl_add_u64 v[28:29], v[24:25], 0, s[100:101]
	global_load_dword v44, v[28:29], off
	global_load_dword v45, v[28:29], off offset:256
	s_mov_b32 s100, 0x3e000
	v_lshl_add_u64 v[30:31], v[26:27], 0, s[100:101]
	v_cvt_pk_bf16_f32 v14, v8, s0
	v_cvt_pk_bf16_f32 v15, v9, s0
	global_store_short v[30:31], v14, off
	global_store_short v[30:31], v15, off offset:128
	v_pk_mul_f32 v[16:17], v[2:3], v[8:9] op_sel:[0,1]
	s_nop 0
	v_pk_fma_f32 v[18:19], v[0:1], v[8:9], v[16:17] neg_lo:[0,0,1] neg_hi:[0,0,1]
	v_pk_fma_f32 v[8:9], v[0:1], v[8:9], v[16:17] op_sel_hi:[1,0,1]
	v_mov_b32_e32 v19, v9
	s_waitcnt vmcnt(46)
	v_pk_add_f32 v[8:9], v[18:19], v[46:47]
	s_mov_b32 s100, 0xac000
	v_lshl_add_u64 v[28:29], v[24:25], 0, s[100:101]
	global_load_dword v46, v[28:29], off
	global_load_dword v47, v[28:29], off offset:256
	s_mov_b32 s100, 0x40000
	v_lshl_add_u64 v[30:31], v[26:27], 0, s[100:101]
	v_cvt_pk_bf16_f32 v14, v8, s0
	v_cvt_pk_bf16_f32 v15, v9, s0
	global_store_short v[30:31], v14, off
	global_store_short v[30:31], v15, off offset:128
	v_pk_mul_f32 v[16:17], v[2:3], v[8:9] op_sel:[0,1]
	s_nop 0
	v_pk_fma_f32 v[18:19], v[0:1], v[8:9], v[16:17] neg_lo:[0,0,1] neg_hi:[0,0,1]
	v_pk_fma_f32 v[8:9], v[0:1], v[8:9], v[16:17] op_sel_hi:[1,0,1]
	v_mov_b32_e32 v19, v9
	s_waitcnt vmcnt(46)
	v_pk_add_f32 v[8:9], v[18:19], v[48:49]
	s_mov_b32 s100, 0xb0000
	v_lshl_add_u64 v[28:29], v[24:25], 0, s[100:101]
	global_load_dword v48, v[28:29], off
	global_load_dword v49, v[28:29], off offset:256
	s_mov_b32 s100, 0x42000
	v_lshl_add_u64 v[30:31], v[26:27], 0, s[100:101]
	v_cvt_pk_bf16_f32 v14, v8, s0
	v_cvt_pk_bf16_f32 v15, v9, s0
	global_store_short v[30:31], v14, off
	global_store_short v[30:31], v15, off offset:128
	v_pk_mul_f32 v[16:17], v[2:3], v[8:9] op_sel:[0,1]
	s_nop 0
	v_pk_fma_f32 v[18:19], v[0:1], v[8:9], v[16:17] neg_lo:[0,0,1] neg_hi:[0,0,1]
	v_pk_fma_f32 v[8:9], v[0:1], v[8:9], v[16:17] op_sel_hi:[1,0,1]
	v_mov_b32_e32 v19, v9
	s_waitcnt vmcnt(46)
	v_pk_add_f32 v[8:9], v[18:19], v[50:51]
	s_mov_b32 s100, 0xb4000
	v_lshl_add_u64 v[28:29], v[24:25], 0, s[100:101]
	global_load_dword v50, v[28:29], off
	global_load_dword v51, v[28:29], off offset:256
	s_mov_b32 s100, 0x44000
	v_lshl_add_u64 v[30:31], v[26:27], 0, s[100:101]
	v_cvt_pk_bf16_f32 v14, v8, s0
	v_cvt_pk_bf16_f32 v15, v9, s0
	global_store_short v[30:31], v14, off
	global_store_short v[30:31], v15, off offset:128
	v_pk_mul_f32 v[16:17], v[2:3], v[8:9] op_sel:[0,1]
	s_nop 0
	v_pk_fma_f32 v[18:19], v[0:1], v[8:9], v[16:17] neg_lo:[0,0,1] neg_hi:[0,0,1]
	v_pk_fma_f32 v[8:9], v[0:1], v[8:9], v[16:17] op_sel_hi:[1,0,1]
	v_mov_b32_e32 v19, v9
	s_waitcnt vmcnt(46)
	v_pk_add_f32 v[8:9], v[18:19], v[52:53]
	s_mov_b32 s100, 0xb8000
	v_lshl_add_u64 v[28:29], v[24:25], 0, s[100:101]
	global_load_dword v52, v[28:29], off
	global_load_dword v53, v[28:29], off offset:256
	s_mov_b32 s100, 0x46000
	v_lshl_add_u64 v[30:31], v[26:27], 0, s[100:101]
	v_cvt_pk_bf16_f32 v14, v8, s0
	v_cvt_pk_bf16_f32 v15, v9, s0
	global_store_short v[30:31], v14, off
	global_store_short v[30:31], v15, off offset:128
	v_pk_mul_f32 v[16:17], v[2:3], v[8:9] op_sel:[0,1]
	s_nop 0
	v_pk_fma_f32 v[18:19], v[0:1], v[8:9], v[16:17] neg_lo:[0,0,1] neg_hi:[0,0,1]
	v_pk_fma_f32 v[8:9], v[0:1], v[8:9], v[16:17] op_sel_hi:[1,0,1]
	v_mov_b32_e32 v19, v9
	s_waitcnt vmcnt(46)
	v_pk_add_f32 v[8:9], v[18:19], v[54:55]
	s_mov_b32 s100, 0xbc000
	v_lshl_add_u64 v[28:29], v[24:25], 0, s[100:101]
	global_load_dword v54, v[28:29], off
	global_load_dword v55, v[28:29], off offset:256
	s_mov_b32 s100, 0x48000
	v_lshl_add_u64 v[30:31], v[26:27], 0, s[100:101]
	v_cvt_pk_bf16_f32 v14, v8, s0
	v_cvt_pk_bf16_f32 v15, v9, s0
	global_store_short v[30:31], v14, off
	global_store_short v[30:31], v15, off offset:128
	v_pk_mul_f32 v[16:17], v[2:3], v[8:9] op_sel:[0,1]
	s_nop 0
	v_pk_fma_f32 v[18:19], v[0:1], v[8:9], v[16:17] neg_lo:[0,0,1] neg_hi:[0,0,1]
	v_pk_fma_f32 v[8:9], v[0:1], v[8:9], v[16:17] op_sel_hi:[1,0,1]
	v_mov_b32_e32 v19, v9
	s_waitcnt vmcnt(46)
; __device__ __forceinline__ unsigned f2bf(float f) { return pk2(f, 0.f) & 0xffffu; }
; __device__ __forceinline__ void ssm_scan(const Args& a, int id) {
;     ...
;     float hr = 0.f, hi = 0.f;
; #pragma unroll 8
;     for (int n = 0; n < 64; ++n) {
;         const size_t base = ((size_t)(b * 64 + n) * 32 + g) * 128;
;         HC[base + p] = (bf16_t)f2bf(hr); HC[base + 64 + p] = (bf16_t)f2bf(hi);
;         const float er = E[base + p], ei = E[base + 64 + p];
;         const float nr = lr * hr - li * hi + er, ni = lr * hi + li * hr + ei;
;         hr = nr; hi = ni;
;     }
	v_pk_add_f32 v[8:9], v[18:19], v[32:33]
	s_mov_b32 s100, 0xc0000
	v_lshl_add_u64 v[28:29], v[24:25], 0, s[100:101]
	global_load_dword v32, v[28:29], off
	global_load_dword v33, v[28:29], off offset:256
	s_mov_b32 s100, 0x4a000
	v_lshl_add_u64 v[30:31], v[26:27], 0, s[100:101]
	v_cvt_pk_bf16_f32 v14, v8, s0
	v_cvt_pk_bf16_f32 v15, v9, s0
	global_store_short v[30:31], v14, off
	global_store_short v[30:31], v15, off offset:128
	v_pk_mul_f32 v[16:17], v[2:3], v[8:9] op_sel:[0,1]
	s_nop 0
	v_pk_fma_f32 v[18:19], v[0:1], v[8:9], v[16:17] neg_lo:[0,0,1] neg_hi:[0,0,1]
	v_pk_fma_f32 v[8:9], v[0:1], v[8:9], v[16:17] op_sel_hi:[1,0,1]
	v_mov_b32_e32 v19, v9
	s_waitcnt vmcnt(46)
	v_pk_add_f32 v[8:9], v[18:19], v[34:35]
	s_mov_b32 s100, 0xc4000
	v_lshl_add_u64 v[28:29], v[24:25], 0, s[100:101]
	global_load_dword v34, v[28:29], off
	global_load_dword v35, v[28:29], off offset:256
	s_mov_b32 s100, 0x4c000
	v_lshl_add_u64 v[30:31], v[26:27], 0, s[100:101]
	v_cvt_pk_bf16_f32 v14, v8, s0
	v_cvt_pk_bf16_f32 v15, v9, s0
	global_store_short v[30:31], v14, off
	global_store_short v[30:31], v15, off offset:128
	v_pk_mul_f32 v[16:17], v[2:3], v[8:9] op_sel:[0,1]
	s_nop 0
	v_pk_fma_f32 v[18:19], v[0:1], v[8:9], v[16:17] neg_lo:[0,0,1] neg_hi:[0,0,1]
	v_pk_fma_f32 v[8:9], v[0:1], v[8:9], v[16:17] op_sel_hi:[1,0,1]
	v_mov_b32_e32 v19, v9
	s_waitcnt vmcnt(46)
	v_pk_add_f32 v[8:9], v[18:19], v[36:37]
	s_mov_b32 s100, 0xc8000
	v_lshl_add_u64 v[28:29], v[24:25], 0, s[100:101]
	global_load_dword v36, v[28:29], off
	global_load_dword v37, v[28:29], off offset:256
	s_mov_b32 s100, 0x4e000
	v_lshl_add_u64 v[30:31], v[26:27], 0, s[100:101]
	v_cvt_pk_bf16_f32 v14, v8, s0
	v_cvt_pk_bf16_f32 v15, v9, s0
	global_store_short v[30:31], v14, off
	global_store_short v[30:31], v15, off offset:128
	v_pk_mul_f32 v[16:17], v[2:3], v[8:9] op_sel:[0,1]
	s_nop 0
	v_pk_fma_f32 v[18:19], v[0:1], v[8:9], v[16:17] neg_lo:[0,0,1] neg_hi:[0,0,1]
	v_pk_fma_f32 v[8:9], v[0:1], v[8:9], v[16:17] op_sel_hi:[1,0,1]
	v_mov_b32_e32 v19, v9
	s_waitcnt vmcnt(46)
	v_pk_add_f32 v[8:9], v[18:19], v[38:39]
	s_mov_b32 s100, 0xcc000
	v_lshl_add_u64 v[28:29], v[24:25], 0, s[100:101]
	global_load_dword v38, v[28:29], off
	global_load_dword v39, v[28:29], off offset:256
	s_mov_b32 s100, 0x50000
	v_lshl_add_u64 v[30:31], v[26:27], 0, s[100:101]
	v_cvt_pk_bf16_f32 v14, v8, s0
	v_cvt_pk_bf16_f32 v15, v9, s0
	global_store_short v[30:31], v14, off
	global_store_short v[30:31], v15, off offset:128
	v_pk_mul_f32 v[16:17], v[2:3], v[8:9] op_sel:[0,1]
	s_nop 0
	v_pk_fma_f32 v[18:19], v[0:1], v[8:9], v[16:17] neg_lo:[0,0,1] neg_hi:[0,0,1]
	v_pk_fma_f32 v[8:9], v[0:1], v[8:9], v[16:17] op_sel_hi:[1,0,1]
	v_mov_b32_e32 v19, v9
	s_waitcnt vmcnt(46)
	v_pk_add_f32 v[8:9], v[18:19], v[40:41]
	s_mov_b32 s100, 0xd0000
	v_lshl_add_u64 v[28:29], v[24:25], 0, s[100:101]
	global_load_dword v40, v[28:29], off
	global_load_dword v41, v[28:29], off offset:256
	s_mov_b32 s100, 0x52000
	v_lshl_add_u64 v[30:31], v[26:27], 0, s[100:101]
	v_cvt_pk_bf16_f32 v14, v8, s0
	v_cvt_pk_bf16_f32 v15, v9, s0
	global_store_short v[30:31], v14, off
	global_store_short v[30:31], v15, off offset:128
	v_pk_mul_f32 v[16:17], v[2:3], v[8:9] op_sel:[0,1]
	s_nop 0
	v_pk_fma_f32 v[18:19], v[0:1], v[8:9], v[16:17] neg_lo:[0,0,1] neg_hi:[0,0,1]
	v_pk_fma_f32 v[8:9], v[0:1], v[8:9], v[16:17] op_sel_hi:[1,0,1]
	v_mov_b32_e32 v19, v9
	s_waitcnt vmcnt(46)
	v_pk_add_f32 v[8:9], v[18:19], v[42:43]
	s_mov_b32 s100, 0xd4000
	v_lshl_add_u64 v[28:29], v[24:25], 0, s[100:101]
	global_load_dword v42, v[28:29], off
	global_load_dword v43, v[28:29], off offset:256
	s_mov_b32 s100, 0x54000
	v_lshl_add_u64 v[30:31], v[26:27], 0, s[100:101]
	v_cvt_pk_bf16_f32 v14, v8, s0
	v_cvt_pk_bf16_f32 v15, v9, s0
	global_store_short v[30:31], v14, off
	global_store_short v[30:31], v15, off offset:128
	v_pk_mul_f32 v[16:17], v[2:3], v[8:9] op_sel:[0,1]
	s_nop 0
	v_pk_fma_f32 v[18:19], v[0:1], v[8:9], v[16:17] neg_lo:[0,0,1] neg_hi:[0,0,1]
	v_pk_fma_f32 v[8:9], v[0:1], v[8:9], v[16:17] op_sel_hi:[1,0,1]
	v_mov_b32_e32 v19, v9
	s_waitcnt vmcnt(46)
	v_pk_add_f32 v[8:9], v[18:19], v[44:45]
	s_mov_b32 s100, 0xd8000
	v_lshl_add_u64 v[28:29], v[24:25], 0, s[100:101]
	global_load_dword v44, v[28:29], off
	global_load_dword v45, v[28:29], off offset:256
	s_mov_b32 s100, 0x56000
	v_lshl_add_u64 v[30:31], v[26:27], 0, s[100:101]
	v_cvt_pk_bf16_f32 v14, v8, s0
	v_cvt_pk_bf16_f32 v15, v9, s0
	global_store_short v[30:31], v14, off
	global_store_short v[30:31], v15, off offset:128
	v_pk_mul_f32 v[16:17], v[2:3], v[8:9] op_sel:[0,1]
	s_nop 0
	v_pk_fma_f32 v[18:19], v[0:1], v[8:9], v[16:17] neg_lo:[0,0,1] neg_hi:[0,0,1]
	v_pk_fma_f32 v[8:9], v[0:1], v[8:9], v[16:17] op_sel_hi:[1,0,1]
	v_mov_b32_e32 v19, v9
	s_waitcnt vmcnt(46)
	v_pk_add_f32 v[8:9], v[18:19], v[46:47]
	s_mov_b32 s100, 0xdc000
	v_lshl_add_u64 v[28:29], v[24:25], 0, s[100:101]
	global_load_dword v46, v[28:29], off
	global_load_dword v47, v[28:29], off offset:256
	s_mov_b32 s100, 0x58000
	v_lshl_add_u64 v[30:31], v[26:27], 0, s[100:101]
	v_cvt_pk_bf16_f32 v14, v8, s0
	v_cvt_pk_bf16_f32 v15, v9, s0
	global_store_short v[30:31], v14, off
	global_store_short v[30:31], v15, off offset:128
	v_pk_mul_f32 v[16:17], v[2:3], v[8:9] op_sel:[0,1]
	s_nop 0
	v_pk_fma_f32 v[18:19], v[0:1], v[8:9], v[16:17] neg_lo:[0,0,1] neg_hi:[0,0,1]
	v_pk_fma_f32 v[8:9], v[0:1], v[8:9], v[16:17] op_sel_hi:[1,0,1]
	v_mov_b32_e32 v19, v9
	s_waitcnt vmcnt(46)
; __device__ __forceinline__ unsigned f2bf(float f) { return pk2(f, 0.f) & 0xffffu; }
; __device__ __forceinline__ void ssm_scan(const Args& a, int id) {
;     ...
;     float hr = 0.f, hi = 0.f;
; #pragma unroll 8
;     for (int n = 0; n < 64; ++n) {
;         const size_t base = ((size_t)(b * 64 + n) * 32 + g) * 128;
;         HC[base + p] = (bf16_t)f2bf(hr); HC[base + 64 + p] = (bf16_t)f2bf(hi);
;         const float er = E[base + p], ei = E[base + 64 + p];
;         const float nr = lr * hr - li * hi + er, ni = lr * hi + li * hr + ei;
;         hr = nr; hi = ni;
;     }
	v_pk_add_f32 v[8:9], v[18:19], v[48:49]
	s_mov_b32 s100, 0xe0000
	v_lshl_add_u64 v[28:29], v[24:25], 0, s[100:101]
	global_load_dword v48, v[28:29], off
	global_load_dword v49, v[28:29], off offset:256
	s_mov_b32 s100, 0x5a000
	v_lshl_add_u64 v[30:31], v[26:27], 0, s[100:101]
	v_cvt_pk_bf16_f32 v14, v8, s0
	v_cvt_pk_bf16_f32 v15, v9, s0
	global_store_short v[30:31], v14, off
	global_store_short v[30:31], v15, off offset:128
	v_pk_mul_f32 v[16:17], v[2:3], v[8:9] op_sel:[0,1]
	s_nop 0
	v_pk_fma_f32 v[18:19], v[0:1], v[8:9], v[16:17] neg_lo:[0,0,1] neg_hi:[0,0,1]
	v_pk_fma_f32 v[8:9], v[0:1], v[8:9], v[16:17] op_sel_hi:[1,0,1]
	v_mov_b32_e32 v19, v9
	s_waitcnt vmcnt(46)
	v_pk_add_f32 v[8:9], v[18:19], v[50:51]
	s_mov_b32 s100, 0xe4000
	v_lshl_add_u64 v[28:29], v[24:25], 0, s[100:101]
	global_load_dword v50, v[28:29], off
	global_load_dword v51, v[28:29], off offset:256
	s_mov_b32 s100, 0x5c000
	v_lshl_add_u64 v[30:31], v[26:27], 0, s[100:101]
	v_cvt_pk_bf16_f32 v14, v8, s0
	v_cvt_pk_bf16_f32 v15, v9, s0
	global_store_short v[30:31], v14, off
	global_store_short v[30:31], v15, off offset:128
	v_pk_mul_f32 v[16:17], v[2:3], v[8:9] op_sel:[0,1]
	s_nop 0
	v_pk_fma_f32 v[18:19], v[0:1], v[8:9], v[16:17] neg_lo:[0,0,1] neg_hi:[0,0,1]
	v_pk_fma_f32 v[8:9], v[0:1], v[8:9], v[16:17] op_sel_hi:[1,0,1]
	v_mov_b32_e32 v19, v9
	s_waitcnt vmcnt(46)
	v_pk_add_f32 v[8:9], v[18:19], v[52:53]
	s_mov_b32 s100, 0xe8000
	v_lshl_add_u64 v[28:29], v[24:25], 0, s[100:101]
	global_load_dword v52, v[28:29], off
	global_load_dword v53, v[28:29], off offset:256
	s_mov_b32 s100, 0x5e000
	v_lshl_add_u64 v[30:31], v[26:27], 0, s[100:101]
	v_cvt_pk_bf16_f32 v14, v8, s0
	v_cvt_pk_bf16_f32 v15, v9, s0
	global_store_short v[30:31], v14, off
	global_store_short v[30:31], v15, off offset:128
	v_pk_mul_f32 v[16:17], v[2:3], v[8:9] op_sel:[0,1]
	s_nop 0
	v_pk_fma_f32 v[18:19], v[0:1], v[8:9], v[16:17] neg_lo:[0,0,1] neg_hi:[0,0,1]
	v_pk_fma_f32 v[8:9], v[0:1], v[8:9], v[16:17] op_sel_hi:[1,0,1]
	v_mov_b32_e32 v19, v9
	s_waitcnt vmcnt(46)
	v_pk_add_f32 v[8:9], v[18:19], v[54:55]
	s_mov_b32 s100, 0xec000
	v_lshl_add_u64 v[28:29], v[24:25], 0, s[100:101]
	global_load_dword v54, v[28:29], off
	global_load_dword v55, v[28:29], off offset:256
	s_mov_b32 s100, 0x60000
	v_lshl_add_u64 v[30:31], v[26:27], 0, s[100:101]
	v_cvt_pk_bf16_f32 v14, v8, s0
	v_cvt_pk_bf16_f32 v15, v9, s0
	global_store_short v[30:31], v14, off
	global_store_short v[30:31], v15, off offset:128
	v_pk_mul_f32 v[16:17], v[2:3], v[8:9] op_sel:[0,1]
	s_nop 0
	v_pk_fma_f32 v[18:19], v[0:1], v[8:9], v[16:17] neg_lo:[0,0,1] neg_hi:[0,0,1]
	v_pk_fma_f32 v[8:9], v[0:1], v[8:9], v[16:17] op_sel_hi:[1,0,1]
	v_mov_b32_e32 v19, v9
	s_waitcnt vmcnt(46)
	v_pk_add_f32 v[8:9], v[18:19], v[32:33]
	s_mov_b32 s100, 0xf0000
	v_lshl_add_u64 v[28:29], v[24:25], 0, s[100:101]
	global_load_dword v32, v[28:29], off
	global_load_dword v33, v[28:29], off offset:256
	s_mov_b32 s100, 0x62000
	v_lshl_add_u64 v[30:31], v[26:27], 0, s[100:101]
	v_cvt_pk_bf16_f32 v14, v8, s0
	v_cvt_pk_bf16_f32 v15, v9, s0
	global_store_short v[30:31], v14, off
	global_store_short v[30:31], v15, off offset:128
	v_pk_mul_f32 v[16:17], v[2:3], v[8:9] op_sel:[0,1]
	s_nop 0
	v_pk_fma_f32 v[18:19], v[0:1], v[8:9], v[16:17] neg_lo:[0,0,1] neg_hi:[0,0,1]
	v_pk_fma_f32 v[8:9], v[0:1], v[8:9], v[16:17] op_sel_hi:[1,0,1]
	v_mov_b32_e32 v19, v9
	s_waitcnt vmcnt(46)
	v_pk_add_f32 v[8:9], v[18:19], v[34:35]
	s_mov_b32 s100, 0xf4000
	v_lshl_add_u64 v[28:29], v[24:25], 0, s[100:101]
	global_load_dword v34, v[28:29], off
	global_load_dword v35, v[28:29], off offset:256
	s_mov_b32 s100, 0x64000
	v_lshl_add_u64 v[30:31], v[26:27], 0, s[100:101]
	v_cvt_pk_bf16_f32 v14, v8, s0
	v_cvt_pk_bf16_f32 v15, v9, s0
	global_store_short v[30:31], v14, off
	global_store_short v[30:31], v15, off offset:128
	v_pk_mul_f32 v[16:17], v[2:3], v[8:9] op_sel:[0,1]
	s_nop 0
	v_pk_fma_f32 v[18:19], v[0:1], v[8:9], v[16:17] neg_lo:[0,0,1] neg_hi:[0,0,1]
	v_pk_fma_f32 v[8:9], v[0:1], v[8:9], v[16:17] op_sel_hi:[1,0,1]
	v_mov_b32_e32 v19, v9
	s_waitcnt vmcnt(46)
	v_pk_add_f32 v[8:9], v[18:19], v[36:37]
	s_mov_b32 s100, 0xf8000
	v_lshl_add_u64 v[28:29], v[24:25], 0, s[100:101]
	global_load_dword v36, v[28:29], off
	global_load_dword v37, v[28:29], off offset:256
	s_mov_b32 s100, 0x66000
	v_lshl_add_u64 v[30:31], v[26:27], 0, s[100:101]
	v_cvt_pk_bf16_f32 v14, v8, s0
	v_cvt_pk_bf16_f32 v15, v9, s0
	global_store_short v[30:31], v14, off
	global_store_short v[30:31], v15, off offset:128
	v_pk_mul_f32 v[16:17], v[2:3], v[8:9] op_sel:[0,1]
	s_nop 0
	v_pk_fma_f32 v[18:19], v[0:1], v[8:9], v[16:17] neg_lo:[0,0,1] neg_hi:[0,0,1]
	v_pk_fma_f32 v[8:9], v[0:1], v[8:9], v[16:17] op_sel_hi:[1,0,1]
	v_mov_b32_e32 v19, v9
	s_waitcnt vmcnt(46)
	v_pk_add_f32 v[8:9], v[18:19], v[38:39]
	s_mov_b32 s100, 0xfc000
	v_lshl_add_u64 v[28:29], v[24:25], 0, s[100:101]
	global_load_dword v38, v[28:29], off
	global_load_dword v39, v[28:29], off offset:256
	s_mov_b32 s100, 0x68000
	v_lshl_add_u64 v[30:31], v[26:27], 0, s[100:101]
	v_cvt_pk_bf16_f32 v14, v8, s0
	v_cvt_pk_bf16_f32 v15, v9, s0
	global_store_short v[30:31], v14, off
	global_store_short v[30:31], v15, off offset:128
	v_pk_mul_f32 v[16:17], v[2:3], v[8:9] op_sel:[0,1]
	s_nop 0
	v_pk_fma_f32 v[18:19], v[0:1], v[8:9], v[16:17] neg_lo:[0,0,1] neg_hi:[0,0,1]
	v_pk_fma_f32 v[8:9], v[0:1], v[8:9], v[16:17] op_sel_hi:[1,0,1]
	v_mov_b32_e32 v19, v9
	s_waitcnt vmcnt(46)
; __device__ __forceinline__ unsigned f2bf(float f) { return pk2(f, 0.f) & 0xffffu; }
; __device__ __forceinline__ void ssm_scan(const Args& a, int id) {
;     ...
;     float hr = 0.f, hi = 0.f;
; #pragma unroll 8
;     for (int n = 0; n < 64; ++n) {
;         const size_t base = ((size_t)(b * 64 + n) * 32 + g) * 128;
;         HC[base + p] = (bf16_t)f2bf(hr); HC[base + 64 + p] = (bf16_t)f2bf(hi);
;         const float er = E[base + p], ei = E[base + 64 + p];
;         const float nr = lr * hr - li * hi + er, ni = lr * hi + li * hr + ei;
;         hr = nr; hi = ni;
;     }
	v_pk_add_f32 v[8:9], v[18:19], v[40:41]
	s_mov_b32 s100, 0x6a000
	v_lshl_add_u64 v[30:31], v[26:27], 0, s[100:101]
	v_cvt_pk_bf16_f32 v14, v8, s0
	v_cvt_pk_bf16_f32 v15, v9, s0
	global_store_short v[30:31], v14, off
	global_store_short v[30:31], v15, off offset:128
	v_pk_mul_f32 v[16:17], v[2:3], v[8:9] op_sel:[0,1]
	s_nop 0
	v_pk_fma_f32 v[18:19], v[0:1], v[8:9], v[16:17] neg_lo:[0,0,1] neg_hi:[0,0,1]
	v_pk_fma_f32 v[8:9], v[0:1], v[8:9], v[16:17] op_sel_hi:[1,0,1]
	v_mov_b32_e32 v19, v9
	s_waitcnt vmcnt(44)
	v_pk_add_f32 v[8:9], v[18:19], v[42:43]
	s_mov_b32 s100, 0x6c000
	v_lshl_add_u64 v[30:31], v[26:27], 0, s[100:101]
	v_cvt_pk_bf16_f32 v14, v8, s0
	v_cvt_pk_bf16_f32 v15, v9, s0
	global_store_short v[30:31], v14, off
	global_store_short v[30:31], v15, off offset:128
	v_pk_mul_f32 v[16:17], v[2:3], v[8:9] op_sel:[0,1]
	s_nop 0
	v_pk_fma_f32 v[18:19], v[0:1], v[8:9], v[16:17] neg_lo:[0,0,1] neg_hi:[0,0,1]
	v_pk_fma_f32 v[8:9], v[0:1], v[8:9], v[16:17] op_sel_hi:[1,0,1]
	v_mov_b32_e32 v19, v9
	s_waitcnt vmcnt(42)
	v_pk_add_f32 v[8:9], v[18:19], v[44:45]
	s_mov_b32 s100, 0x6e000
	v_lshl_add_u64 v[30:31], v[26:27], 0, s[100:101]
	v_cvt_pk_bf16_f32 v14, v8, s0
	v_cvt_pk_bf16_f32 v15, v9, s0
	global_store_short v[30:31], v14, off
	global_store_short v[30:31], v15, off offset:128
	v_pk_mul_f32 v[16:17], v[2:3], v[8:9] op_sel:[0,1]
	s_nop 0
	v_pk_fma_f32 v[18:19], v[0:1], v[8:9], v[16:17] neg_lo:[0,0,1] neg_hi:[0,0,1]
	v_pk_fma_f32 v[8:9], v[0:1], v[8:9], v[16:17] op_sel_hi:[1,0,1]
	v_mov_b32_e32 v19, v9
	s_waitcnt vmcnt(40)
	v_pk_add_f32 v[8:9], v[18:19], v[46:47]
	s_mov_b32 s100, 0x70000
	v_lshl_add_u64 v[30:31], v[26:27], 0, s[100:101]
	v_cvt_pk_bf16_f32 v14, v8, s0
	v_cvt_pk_bf16_f32 v15, v9, s0
	global_store_short v[30:31], v14, off
	global_store_short v[30:31], v15, off offset:128
	v_pk_mul_f32 v[16:17], v[2:3], v[8:9] op_sel:[0,1]
	s_nop 0
	v_pk_fma_f32 v[18:19], v[0:1], v[8:9], v[16:17] neg_lo:[0,0,1] neg_hi:[0,0,1]
	v_pk_fma_f32 v[8:9], v[0:1], v[8:9], v[16:17] op_sel_hi:[1,0,1]
	v_mov_b32_e32 v19, v9
	s_waitcnt vmcnt(38)
	v_pk_add_f32 v[8:9], v[18:19], v[48:49]
	s_mov_b32 s100, 0x72000
	v_lshl_add_u64 v[30:31], v[26:27], 0, s[100:101]
	v_cvt_pk_bf16_f32 v14, v8, s0
	v_cvt_pk_bf16_f32 v15, v9, s0
	global_store_short v[30:31], v14, off
	global_store_short v[30:31], v15, off offset:128
	v_pk_mul_f32 v[16:17], v[2:3], v[8:9] op_sel:[0,1]
	s_nop 0
	v_pk_fma_f32 v[18:19], v[0:1], v[8:9], v[16:17] neg_lo:[0,0,1] neg_hi:[0,0,1]
	v_pk_fma_f32 v[8:9], v[0:1], v[8:9], v[16:17] op_sel_hi:[1,0,1]
	v_mov_b32_e32 v19, v9
	s_waitcnt vmcnt(36)
	v_pk_add_f32 v[8:9], v[18:19], v[50:51]
	s_mov_b32 s100, 0x74000
	v_lshl_add_u64 v[30:31], v[26:27], 0, s[100:101]
	v_cvt_pk_bf16_f32 v14, v8, s0
	v_cvt_pk_bf16_f32 v15, v9, s0
	global_store_short v[30:31], v14, off
	global_store_short v[30:31], v15, off offset:128
	v_pk_mul_f32 v[16:17], v[2:3], v[8:9] op_sel:[0,1]
	s_nop 0
	v_pk_fma_f32 v[18:19], v[0:1], v[8:9], v[16:17] neg_lo:[0,0,1] neg_hi:[0,0,1]
	v_pk_fma_f32 v[8:9], v[0:1], v[8:9], v[16:17] op_sel_hi:[1,0,1]
	v_mov_b32_e32 v19, v9
	s_waitcnt vmcnt(34)
	v_pk_add_f32 v[8:9], v[18:19], v[52:53]
	s_mov_b32 s100, 0x76000
	v_lshl_add_u64 v[30:31], v[26:27], 0, s[100:101]
	v_cvt_pk_bf16_f32 v14, v8, s0
	v_cvt_pk_bf16_f32 v15, v9, s0
	global_store_short v[30:31], v14, off
	global_store_short v[30:31], v15, off offset:128
	v_pk_mul_f32 v[16:17], v[2:3], v[8:9] op_sel:[0,1]
	s_nop 0
	v_pk_fma_f32 v[18:19], v[0:1], v[8:9], v[16:17] neg_lo:[0,0,1] neg_hi:[0,0,1]
	v_pk_fma_f32 v[8:9], v[0:1], v[8:9], v[16:17] op_sel_hi:[1,0,1]
	v_mov_b32_e32 v19, v9
	s_waitcnt vmcnt(32)
	v_pk_add_f32 v[8:9], v[18:19], v[54:55]
	s_mov_b32 s100, 0x78000
	v_lshl_add_u64 v[30:31], v[26:27], 0, s[100:101]
	v_cvt_pk_bf16_f32 v14, v8, s0
	v_cvt_pk_bf16_f32 v15, v9, s0
	global_store_short v[30:31], v14, off
	global_store_short v[30:31], v15, off offset:128
	v_pk_mul_f32 v[16:17], v[2:3], v[8:9] op_sel:[0,1]
	s_nop 0
	v_pk_fma_f32 v[18:19], v[0:1], v[8:9], v[16:17] neg_lo:[0,0,1] neg_hi:[0,0,1]
	v_pk_fma_f32 v[8:9], v[0:1], v[8:9], v[16:17] op_sel_hi:[1,0,1]
	v_mov_b32_e32 v19, v9
	s_waitcnt vmcnt(30)
	v_pk_add_f32 v[8:9], v[18:19], v[32:33]
	s_mov_b32 s100, 0x7a000
	v_lshl_add_u64 v[30:31], v[26:27], 0, s[100:101]
	v_cvt_pk_bf16_f32 v14, v8, s0
	v_cvt_pk_bf16_f32 v15, v9, s0
	global_store_short v[30:31], v14, off
	global_store_short v[30:31], v15, off offset:128
	v_pk_mul_f32 v[16:17], v[2:3], v[8:9] op_sel:[0,1]
	s_nop 0
	v_pk_fma_f32 v[18:19], v[0:1], v[8:9], v[16:17] neg_lo:[0,0,1] neg_hi:[0,0,1]
	v_pk_fma_f32 v[8:9], v[0:1], v[8:9], v[16:17] op_sel_hi:[1,0,1]
	v_mov_b32_e32 v19, v9
	s_waitcnt vmcnt(28)
	v_pk_add_f32 v[8:9], v[18:19], v[34:35]
	s_mov_b32 s100, 0x7c000
	v_lshl_add_u64 v[30:31], v[26:27], 0, s[100:101]
	v_cvt_pk_bf16_f32 v14, v8, s0
	v_cvt_pk_bf16_f32 v15, v9, s0
	global_store_short v[30:31], v14, off
	global_store_short v[30:31], v15, off offset:128
	v_pk_mul_f32 v[16:17], v[2:3], v[8:9] op_sel:[0,1]
	s_nop 0
	v_pk_fma_f32 v[18:19], v[0:1], v[8:9], v[16:17] neg_lo:[0,0,1] neg_hi:[0,0,1]
	v_pk_fma_f32 v[8:9], v[0:1], v[8:9], v[16:17] op_sel_hi:[1,0,1]
	v_mov_b32_e32 v19, v9
	s_waitcnt vmcnt(26)
	v_pk_add_f32 v[8:9], v[18:19], v[36:37]
	s_mov_b32 s100, 0x7e000
	v_lshl_add_u64 v[30:31], v[26:27], 0, s[100:101]
	v_cvt_pk_bf16_f32 v14, v8, s0
	v_cvt_pk_bf16_f32 v15, v9, s0
	global_store_short v[30:31], v14, off
	global_store_short v[30:31], v15, off offset:128
	v_pk_mul_f32 v[16:17], v[2:3], v[8:9] op_sel:[0,1]
	s_nop 0
	v_pk_fma_f32 v[18:19], v[0:1], v[8:9], v[16:17] neg_lo:[0,0,1] neg_hi:[0,0,1]
	v_pk_fma_f32 v[8:9], v[0:1], v[8:9], v[16:17] op_sel_hi:[1,0,1]
	v_mov_b32_e32 v19, v9
	s_waitcnt vmcnt(24)
	v_pk_add_f32 v[8:9], v[18:19], v[38:39]
